# k30 + layer-0 residual row loop: next-row prefetch waited at the loop bottom (counted) instead of right after issue
# baseline (speedup 1.0000x reference)
; __device__ __forceinline__ void resid_rows(const float* xf_, bf16_t* XB_, const bf16_t* Y_, const float* gain_, float* R_, float* outf_, int rows, int gw, int NGW, int lane) {
;     ...
;     RR_LOAD(xw, yw, xv, gw);
;     for (int row = gw; row < rows; row += NGW) {
;         RR_LOAD(nxw, nyw, nxv, row + NGW);
;     ...
;         xw[0] = nxw[0]; xw[1] = nxw[1]; yw[0] = nyw[0]; yw[1] = nyw[1]; xv[0] = nxv[0]; xv[1] = nxv[1]; xv[2] = nxv[2]; xv[3] = nxv[3];
.LBB0_210:
	s_cmpk_gt_i32 s0, 0x7fff
	s_cbranch_scc1 .LBB0_223
	s_ashr_i32 s1, s0, 31
	s_lshl_b64 s[18:19], s[0:1], 2
	s_add_u32 s3, s12, s18
	s_addc_u32 s7, s13, s19
	s_add_u32 s12, s3, 0x30840000
	s_addc_u32 s13, s7, 0
	s_ashr_i32 s3, s2, 31
	s_lshl_b64 s[18:19], s[2:3], 2
	s_lshl_b64 s[20:21], s[0:1], 11
	s_add_u32 s20, s4, s20
	v_cmp_eq_u32_e64 s[40:41], 0, v64
	s_addc_u32 s21, s5, s21
	s_lshl_b64 s[22:23], s[2:3], 11
	s_waitcnt vmcnt(0)
	s_branch .LBB0_213
.LBB0_212:
	s_or_b64 exec, exec, s[28:29]
	s_waitcnt vmcnt(2)
	s_add_u32 s12, s12, s18
	s_addc_u32 s13, s13, s19
	s_add_u32 s20, s20, s22
	s_addc_u32 s21, s21, s23
	v_mov_b64_e32 v[42:43], v[22:23]
	v_mov_b64_e32 v[46:47], v[18:19]
	v_mov_b64_e32 v[4:5], v[36:37]
	v_mov_b64_e32 v[8:9], v[32:33]
	v_mov_b64_e32 v[0:1], v[28:29]
	v_mov_b64_e32 v[12:13], v[24:25]
	v_mov_b64_e32 v[50:51], v[38:39]
	v_mov_b64_e32 v[54:55], v[34:35]
	v_mov_b64_e32 v[58:59], v[30:31]
	v_mov_b64_e32 v[62:63], v[26:27]
	s_cmpk_gt_i32 s0, 0x7fff
	v_mov_b64_e32 v[40:41], v[20:21]
	v_mov_b64_e32 v[44:45], v[16:17]
	v_mov_b64_e32 v[6:7], v[38:39]
	v_mov_b64_e32 v[10:11], v[34:35]
	v_mov_b64_e32 v[2:3], v[30:31]
	v_mov_b64_e32 v[14:15], v[26:27]
	v_mov_b64_e32 v[48:49], v[36:37]
	v_mov_b64_e32 v[52:53], v[32:33]
	v_mov_b64_e32 v[56:57], v[28:29]
	v_mov_b64_e32 v[60:61], v[24:25]
	s_cbranch_scc1 .LBB0_223

; __device__ __forceinline__ unsigned cvt_pk_bf16(float lo, float hi) { unsigned r; asm volatile("v_cvt_pk_bf16_f32 %0, %1, %2" : "=v"(r) : "v"(lo), "v"(hi)); return r; }
; #define GASF __attribute__((address_space(1)))
; __device__ __forceinline__ void resid_rows(const float* xf_, bf16_t* XB_, const bf16_t* Y_, const float* gain_, float* R_, float* outf_, int rows, int gw, int NGW, int lane) {
;     ...
;         else { GASF u32x4* p = (GASF u32x4*)(XB_ + (size_t)row * DM); float ss = 0.f;
; #pragma unroll
;             for (int i = 0; i < 16; ++i) ss += v[i] * v[i];
; #pragma unroll
;             for (int j = 0; j < 2; ++j) { u32x4 w; w.x = cvt_pk_bf16(v[8 * j + 0], v[8 * j + 1]); w.y = cvt_pk_bf16(v[8 * j + 2], v[8 * j + 3]); w.z = cvt_pk_bf16(v[8 * j + 4], v[8 * j + 5]); w.w = cvt_pk_bf16(v[8 * j + 6], v[8 * j + 7]); p[lane + 64 * j] = w; }
;             ss = wave_sum(ss);
;             if (lane == 0) ((GASF float*)R_)[row] = 1.0f / sqrtf(ss * (1.f / DM) + EPS); }
.LBB0_219:
	s_nop 0
	v_mul_f32_e32 v40, v13, v13
	v_fmac_f32_e32 v40, v12, v12
	v_fmac_f32_e32 v40, v14, v14
	v_fmac_f32_e32 v40, v15, v15
	v_fmac_f32_e32 v40, v0, v0
	v_fmac_f32_e32 v40, v1, v1
	v_fmac_f32_e32 v40, v2, v2
	v_fmac_f32_e32 v40, v3, v3
	v_fmac_f32_e32 v40, v8, v8
	v_fmac_f32_e32 v40, v9, v9
	v_fmac_f32_e32 v40, v10, v10
	v_fmac_f32_e32 v40, v11, v11
	v_fmac_f32_e32 v40, v4, v4
	v_fmac_f32_e32 v40, v5, v5
	v_fmac_f32_e32 v40, v6, v6
	v_fmac_f32_e32 v40, v7, v7
	ds_swizzle_b32 v41, v40 offset:swizzle(SWAP,1)
	v_cvt_pk_bf16_f32 v12, v12, v13
	v_cvt_pk_bf16_f32 v13, v14, v15
	v_cvt_pk_bf16_f32 v14, v0, v1
	v_cvt_pk_bf16_f32 v15, v2, v3
	s_waitcnt lgkmcnt(0)
	v_add_f32_e32 v40, v40, v41
	ds_swizzle_b32 v41, v40 offset:swizzle(SWAP,2)
	s_waitcnt lgkmcnt(0)
	v_add_f32_e32 v40, v40, v41
	ds_swizzle_b32 v41, v40 offset:swizzle(SWAP,4)
	s_waitcnt lgkmcnt(0)
	v_add_f32_e32 v1, v40, v41
	ds_swizzle_b32 v42, v1 offset:swizzle(SWAP,8)
	v_lshl_add_u64 v[40:41], v[64:65], 4, s[20:21]
	global_store_dwordx4 v[40:41], v[12:15], off
	v_cvt_pk_bf16_f32 v0, v8, v9
	s_waitcnt lgkmcnt(0)
	v_add_f32_e32 v8, v1, v42
	ds_swizzle_b32 v9, v8 offset:swizzle(SWAP,16)
	v_cvt_pk_bf16_f32 v1, v10, v11
	v_cvt_pk_bf16_f32 v2, v4, v5
	v_cvt_pk_bf16_f32 v3, v6, v7
	global_store_dwordx4 v[40:41], v[0:3], off offset:1024
	s_waitcnt lgkmcnt(0)
	s_nop 0
	v_add_f32_e32 v0, v8, v9
	v_mov_b32_e32 v1, v0
	s_nop 1
	v_permlane32_swap_b32_e32 v0, v1
	s_and_saveexec_b64 s[28:29], s[40:41]
	s_cbranch_execz .LBB0_212
	v_add_f32_e32 v0, v0, v1
	v_fmamk_f32 v0, v0, 0x3a800000, v204
	v_mul_f32_e32 v1, 0x4f800000, v0
	v_cmp_gt_f32_e32 vcc, s81, v0
	s_nop 1
	v_cndmask_b32_e32 v0, v0, v1, vcc
	v_sqrt_f32_e32 v1, v0
	s_nop 0
	v_add_u32_e32 v2, -1, v1
	v_fma_f32 v4, -v2, v1, v0
	v_add_u32_e32 v3, 1, v1
	v_cmp_ge_f32_e64 s[42:43], 0, v4
	s_nop 1
	v_cndmask_b32_e64 v2, v1, v2, s[42:43]
	v_fma_f32 v1, -v3, v1, v0
	v_cmp_lt_f32_e64 s[42:43], 0, v1
	s_nop 1
	v_cndmask_b32_e64 v1, v2, v3, s[42:43]
	v_mul_f32_e32 v2, 0x37800000, v1
	v_cndmask_b32_e32 v1, v1, v2, vcc
	v_cmp_class_f32_e32 vcc, v0, v205
	s_nop 1
	v_cndmask_b32_e32 v0, v1, v0, vcc
	v_div_scale_f32 v1, s[30:31], v0, v0, 1.0
	v_rcp_f32_e32 v2, v1
	s_nop 0
	v_fma_f32 v3, -v1, v2, 1.0
	v_fmac_f32_e32 v2, v3, v2
	v_div_scale_f32 v3, vcc, 1.0, v0, 1.0
	v_mul_f32_e32 v4, v3, v2
	v_fma_f32 v5, -v1, v4, v3
	v_fmac_f32_e32 v4, v5, v2
	v_fma_f32 v1, -v1, v4, v3
	v_div_fmas_f32 v1, v1, v2, v4
	v_div_fixup_f32 v0, v1, v0, 1.0
	global_store_dword v175, v0, s[12:13]
	s_branch .LBB0_212
